# token barrier: wave 7 performs sb_arrive atomics so wave 0 polls the next token concurrently
# speedup vs baseline: 1.0024x; 1.0024x over previous
.LBB0_61:
	v_cndmask_b32_e64 v0, 0, 1, s[22:23]
	s_waitcnt vmcnt(0)
	v_cmp_ne_u32_e64 s[0:1], 1, v0
	s_andn2_b64 vcc, exec, s[22:23]
	s_waitcnt lgkmcnt(0)
	v_writelane_b32 v255, s0, 10
	s_barrier
	s_nop 0
	v_writelane_b32 v255, s1, 11
	s_nop 0
	v_readlane_b32 s70, v255, 9
	s_cmp_lg_u32 s70, 7
	s_cselect_b64 s[70:71], -1, 0
	v_writelane_b32 v255, s70, 60
	v_writelane_b32 v255, s71, 61
	s_cbranch_vccnz .LBB0_107
	v_mbcnt_lo_u32_b32 v0, -1, 0
	v_mbcnt_hi_u32_b32 v0, -1, v0
	s_nop 0
	v_cmp_eq_u32_e32 vcc, 0, v0
	s_and_saveexec_b64 s[38:39], vcc
	s_cbranch_execz .LBB0_106
	s_add_i32 s1, 0, 0x20160
	s_mov_b32 s0, s86
	v_mov_b32_e32 v0, s1
	s_waitcnt vmcnt(0) expcnt(0) lgkmcnt(0)
	ds_read_b32 v2, v0
	s_add_i32 s1, 0, 0x20164
	v_mov_b32_e32 v0, s1
	ds_read_b32 v0, v0
	s_waitcnt lgkmcnt(1)
	v_cmp_ne_u32_e32 vcc, 0, v2
	s_cbranch_vccnz .LBB0_77
	s_add_u32 s6, s36, 0x1000
	s_addc_u32 s7, s37, 0
	s_load_dwordx2 s[2:3], s[20:21], 0x4
	s_add_u32 s8, s36, 0x1100
	s_addc_u32 s9, s37, 0
	s_add_u32 s10, s36, 0x1200
	s_addc_u32 s11, s37, 0
	s_add_u32 s12, s36, 0x1300
	s_waitcnt lgkmcnt(0)
	s_mul_i32 s1, s2, s59
	s_addc_u32 s13, s37, 0
	s_mul_i32 s1, s1, s3
	s_mov_b32 s2, 1
	s_mov_b64 s[4:5], 0
	v_mov_b64_e32 v[0:1], s[36:37]
	v_mov_b64_e32 v[2:3], s[6:7]
	v_mov_b64_e32 v[4:5], s[8:9]
	v_mov_b64_e32 v[6:7], s[10:11]
	v_mov_b64_e32 v[8:9], s[12:13]
	s_branch .LBB0_67

.LBB0_171:
	s_waitcnt vmcnt(0)
	v_readlane_b32 s0, v255, 60
	v_readlane_b32 s1, v255, 61
	s_and_b64 vcc, exec, s[0:1]
	s_waitcnt vmcnt(0)
	s_barrier
	s_cbranch_vccnz .LBB0_113
	v_mbcnt_lo_u32_b32 v0, -1, 0
	v_mbcnt_hi_u32_b32 v0, -1, v0
	s_nop 0
	v_cmp_eq_u32_e32 vcc, 0, v0
	s_and_saveexec_b64 s[4:5], vcc
	s_cbranch_execz .LBB0_112
	s_mul_i32 s1, s63, 0x220
	v_readlane_b32 s2, v255, 12
	s_mul_hi_i32 s0, s63, 0x220
	s_add_u32 s8, s2, s1
	v_readlane_b32 s1, v255, 13
	s_addc_u32 s9, s1, s0
	s_mov_b32 s0, s86
	v_readlane_b32 s1, v255, 19
	s_lshl_b32 s56, s0, 3
	s_waitcnt vmcnt(0) expcnt(0) lgkmcnt(0)
	v_mov_b32_e32 v0, s1
	s_lshl_b64 s[0:1], s[56:57], 2
	s_add_u32 s0, s8, s0
	s_addc_u32 s1, s9, s1
	v_mov_b64_e32 v[2:3], s[0:1]
	ds_read_b32 v0, v0
	flat_atomic_add v2, v[2:3], v201 sc0
	s_waitcnt vmcnt(0) lgkmcnt(0)
	v_add_u32_e32 v2, 1, v2
	v_cmp_eq_u32_e32 vcc, v2, v0
	s_and_b64 exec, exec, vcc
	s_cbranch_execz .LBB0_112
	buffer_wbl2 sc1
	s_waitcnt vmcnt(0)
	v_mov_b64_e32 v[2:3], s[8:9]
	flat_atomic_add v[2:3], v201 offset:512
	s_branch .LBB0_112

.LBB0_232:
	s_waitcnt vmcnt(0) lgkmcnt(0)
	s_barrier
	s_waitcnt vmcnt(0)
	v_readlane_b32 s0, v255, 60
	v_readlane_b32 s1, v255, 61
	v_readlane_b32 s88, v255, 22
	v_readlane_b32 s92, v255, 24
	s_and_b64 vcc, exec, s[0:1]
	v_readlane_b32 s89, v255, 23
	v_readlane_b32 s93, v255, 25
	v_readlane_b32 s94, v255, 26
	v_readlane_b32 s95, v255, 27
	s_waitcnt vmcnt(0) lgkmcnt(0)
	s_barrier
	s_cbranch_vccnz .LBB0_179
	v_mbcnt_lo_u32_b32 v0, -1, 0
	v_mbcnt_hi_u32_b32 v0, -1, v0
	s_nop 0
	v_cmp_eq_u32_e32 vcc, 0, v0
	s_and_saveexec_b64 s[4:5], vcc
	s_cbranch_execz .LBB0_178
	s_mul_i32 s1, s62, 0x220
	v_readlane_b32 s2, v255, 12
	s_mul_hi_i32 s0, s62, 0x220
	s_add_u32 s6, s2, s1
	v_readlane_b32 s1, v255, 13
	s_addc_u32 s7, s1, s0
	s_mov_b32 s0, s86
	v_readlane_b32 s1, v255, 19
	s_lshl_b32 s56, s0, 3
	s_waitcnt vmcnt(0) expcnt(0) lgkmcnt(0)
	v_mov_b32_e32 v0, s1
	s_lshl_b64 s[0:1], s[56:57], 2
	s_add_u32 s0, s6, s0
	s_addc_u32 s1, s7, s1
	v_mov_b64_e32 v[2:3], s[0:1]
	ds_read_b32 v0, v0
	flat_atomic_add v2, v[2:3], v201 sc0
	s_waitcnt vmcnt(0) lgkmcnt(0)
	v_add_u32_e32 v2, 1, v2
	v_cmp_eq_u32_e32 vcc, v2, v0
	s_and_b64 exec, exec, vcc
	s_cbranch_execz .LBB0_178
	buffer_wbl2 sc1
	s_waitcnt vmcnt(0)
	v_mov_b64_e32 v[2:3], s[6:7]
	flat_atomic_add v[2:3], v201 offset:512
	s_branch .LBB0_178

.LBB0_283:
	s_waitcnt vmcnt(0) lgkmcnt(0)
	s_barrier
	s_waitcnt vmcnt(0)
	v_readlane_b32 s0, v255, 60
	v_readlane_b32 s1, v255, 61
	s_and_b64 vcc, exec, s[0:1]
	s_waitcnt vmcnt(0) lgkmcnt(0)
	s_barrier
	s_cbranch_vccnz .LBB0_240
	v_mbcnt_lo_u32_b32 v0, -1, 0
	v_mbcnt_hi_u32_b32 v0, -1, v0
	s_nop 0
	v_cmp_eq_u32_e32 vcc, 0, v0
	s_and_saveexec_b64 s[4:5], vcc
	s_cbranch_execz .LBB0_239
	s_mul_i32 s1, s63, 0x220
	v_readlane_b32 s2, v255, 12
	s_mul_hi_i32 s0, s63, 0x220
	s_add_u32 s6, s2, s1
	v_readlane_b32 s1, v255, 13
	s_addc_u32 s7, s1, s0
	s_mov_b32 s0, s86
	v_readlane_b32 s1, v255, 19
	s_lshl_b32 s56, s0, 3
	s_waitcnt vmcnt(0) expcnt(0) lgkmcnt(0)
	v_mov_b32_e32 v0, s1
	s_lshl_b64 s[0:1], s[56:57], 2
	s_add_u32 s0, s6, s0
	s_addc_u32 s1, s7, s1
	v_mov_b64_e32 v[2:3], s[0:1]
	ds_read_b32 v0, v0
	flat_atomic_add v2, v[2:3], v201 sc0
	s_waitcnt vmcnt(0) lgkmcnt(0)
	v_add_u32_e32 v2, 1, v2
	v_cmp_eq_u32_e32 vcc, v2, v0
	s_and_b64 exec, exec, vcc
	s_cbranch_execz .LBB0_239
	buffer_wbl2 sc1
	s_waitcnt vmcnt(0)
	v_mov_b64_e32 v[2:3], s[6:7]
	flat_atomic_add v[2:3], v201 offset:512
	s_branch .LBB0_239

.LBB0_331:
	s_waitcnt vmcnt(0)
	v_readlane_b32 s0, v255, 60
	v_readlane_b32 s1, v255, 61
	s_and_b64 vcc, exec, s[0:1]
	s_waitcnt lgkmcnt(0)
	s_barrier
	s_cbranch_vccnz .LBB0_289
	v_mbcnt_lo_u32_b32 v0, -1, 0
	v_mbcnt_hi_u32_b32 v0, -1, v0
	s_nop 0
	v_cmp_eq_u32_e32 vcc, 0, v0
	s_and_saveexec_b64 s[4:5], vcc
	s_cbranch_execz .LBB0_288
	s_mul_i32 s1, s63, 0x220
	v_readlane_b32 s2, v255, 12
	s_mul_hi_i32 s0, s63, 0x220
	s_add_u32 s6, s2, s1
	v_readlane_b32 s1, v255, 13
	s_addc_u32 s7, s1, s0
	s_mov_b32 s0, s86
	v_readlane_b32 s1, v255, 19
	s_lshl_b32 s56, s0, 3
	s_waitcnt vmcnt(0) expcnt(0) lgkmcnt(0)
	v_mov_b32_e32 v0, s1
	s_lshl_b64 s[0:1], s[56:57], 2
	s_add_u32 s0, s6, s0
	s_addc_u32 s1, s7, s1
	v_mov_b64_e32 v[2:3], s[0:1]
	ds_read_b32 v0, v0
	flat_atomic_add v2, v[2:3], v201 sc0
	s_waitcnt vmcnt(0) lgkmcnt(0)
	v_add_u32_e32 v2, 1, v2
	v_cmp_eq_u32_e32 vcc, v2, v0
	s_and_b64 exec, exec, vcc
	s_cbranch_execz .LBB0_288
	buffer_wbl2 sc1
	s_waitcnt vmcnt(0)
	v_mov_b64_e32 v[2:3], s[6:7]
	flat_atomic_add v[2:3], v201 offset:512
	s_branch .LBB0_288

.LBB0_407:
	s_waitcnt vmcnt(0)
	v_readlane_b32 s4, v255, 60
	v_readlane_b32 s5, v255, 61
	s_and_b64 vcc, exec, s[4:5]
	s_waitcnt lgkmcnt(0)
	s_barrier
	s_cbranch_vccnz .LBB0_339
	v_mbcnt_lo_u32_b32 v0, -1, 0
	v_mbcnt_hi_u32_b32 v0, -1, v0
	s_nop 0
	v_cmp_eq_u32_e32 vcc, 0, v0
	s_and_saveexec_b64 s[4:5], vcc
	s_cbranch_execz .LBB0_338
	s_mul_i32 s6, s26, 0x220
	v_readlane_b32 s7, v255, 12
	s_mul_hi_i32 s3, s26, 0x220
	s_add_u32 s6, s7, s6
	v_readlane_b32 s7, v255, 13
	s_addc_u32 s7, s7, s3
	s_mov_b32 s3, s86
	v_readlane_b32 s8, v255, 19
	s_lshl_b32 s56, s3, 3
	s_waitcnt vmcnt(0) expcnt(0) lgkmcnt(0)
	v_mov_b32_e32 v0, s8
	s_lshl_b64 s[8:9], s[56:57], 2
	s_add_u32 s8, s6, s8
	s_addc_u32 s9, s7, s9
	v_mov_b64_e32 v[2:3], s[8:9]
	ds_read_b32 v0, v0
	flat_atomic_add v2, v[2:3], v201 sc0
	s_waitcnt vmcnt(0) lgkmcnt(0)
	v_add_u32_e32 v2, 1, v2
	v_cmp_eq_u32_e32 vcc, v2, v0
	s_and_b64 exec, exec, vcc
	s_cbranch_execz .LBB0_338
	buffer_wbl2 sc1
	s_waitcnt vmcnt(0)
	v_mov_b64_e32 v[2:3], s[6:7]
	flat_atomic_add v[2:3], v201 offset:512
	s_branch .LBB0_338

.LBB0_432:
	s_waitcnt vmcnt(0)
	v_readlane_b32 s0, v255, 60
	v_readlane_b32 s1, v255, 61
	s_and_b64 vcc, exec, s[0:1]
	s_waitcnt lgkmcnt(0)
	s_barrier
	s_cbranch_vccnz .LBB0_437
	v_mbcnt_lo_u32_b32 v0, -1, 0
	v_mbcnt_hi_u32_b32 v0, -1, v0
	s_mov_b32 s9, 0
	v_cmp_eq_u32_e32 vcc, 0, v0
	s_and_saveexec_b64 s[4:5], vcc
	s_cbranch_execz .LBB0_436
	s_mul_i32 s1, s63, 0x220
	v_readlane_b32 s2, v255, 12
	s_mul_hi_i32 s0, s63, 0x220
	s_add_u32 s6, s2, s1
	v_readlane_b32 s1, v255, 13
	s_addc_u32 s7, s1, s0
	s_mov_b32 s0, s86
	s_add_i32 s1, 0, 0x20160
	s_lshl_b32 s8, s0, 3
	v_mov_b32_e32 v0, s1
	s_lshl_b64 s[0:1], s[8:9], 2
	s_add_u32 s0, s6, s0
	s_addc_u32 s1, s7, s1
	s_waitcnt vmcnt(0) expcnt(0) lgkmcnt(0)
	ds_read_b32 v1, v0
	v_mov_b32_e32 v0, 1
	v_mov_b64_e32 v[2:3], s[0:1]
	flat_atomic_add v2, v[2:3], v0 sc0
	s_waitcnt vmcnt(0) lgkmcnt(0)
	v_add_u32_e32 v2, 1, v2
	v_cmp_eq_u32_e32 vcc, v2, v1
	s_and_b64 exec, exec, vcc
	s_cbranch_execz .LBB0_436
	buffer_wbl2 sc1
	s_waitcnt vmcnt(0)
	v_mov_b64_e32 v[2:3], s[6:7]
	flat_atomic_add v[2:3], v0 offset:512

.LBB0_458:
	s_waitcnt vmcnt(0)
	v_readlane_b32 s0, v255, 60
	v_readlane_b32 s1, v255, 61
	s_and_b64 vcc, exec, s[0:1]
	s_waitcnt lgkmcnt(0)
	s_barrier
	s_cbranch_vccnz .LBB0_462
	v_mbcnt_lo_u32_b32 v0, -1, 0
	v_mbcnt_hi_u32_b32 v0, -1, v0
	s_mov_b32 s3, 0
	v_cmp_eq_u32_e32 vcc, 0, v0
	s_and_saveexec_b64 s[0:1], vcc
	s_cbranch_execz .LBB0_462
	s_add_i32 s0, s26, 2
	s_mul_hi_i32 s1, s0, 0x220
	s_mulk_i32 s0, 0x220
	v_readlane_b32 s2, v255, 12
	s_add_u32 s0, s2, s0
	v_readlane_b32 s2, v255, 13
	s_addc_u32 s1, s2, s1
	s_add_i32 s2, 0, 0x20160
	v_mov_b32_e32 v0, s2
	s_lshl_b32 s2, s86, 3
	s_lshl_b64 s[2:3], s[2:3], 2
	s_add_u32 s2, s0, s2
	s_addc_u32 s3, s1, s3
	s_waitcnt vmcnt(0) expcnt(0) lgkmcnt(0)
	ds_read_b32 v1, v0
	v_mov_b32_e32 v0, 1
	v_mov_b64_e32 v[2:3], s[2:3]
	flat_atomic_add v2, v[2:3], v0 sc0
	s_waitcnt vmcnt(0) lgkmcnt(0)
	v_add_u32_e32 v2, 1, v2
	v_cmp_eq_u32_e32 vcc, v2, v1
	s_and_b64 exec, exec, vcc
	s_cbranch_execz .LBB0_462
	buffer_wbl2 sc1
	s_waitcnt vmcnt(0)
	v_mov_b64_e32 v[2:3], s[0:1]
	flat_atomic_add v[2:3], v0 offset:512
